# v12_gatemfma
# speedup vs baseline: 1.0611x; 1.0479x over previous
; DEVI void moba_item(const Params& p, int l, int item) {
;   const int tid_ = get_tid();
;   const int bh = item & 15, r = item >> 4;
;   const int qt = (r < 16) ? 31 - r : r - 16;
;   const int b = bh >> 3, h = bh & 7, qblk = qt >> 1;
;   const long t0 = (long)b * S_ + qt * 128;
;   const int tid = tid_, w = tid >> 6, lane = tid & 63, fr = lane & 15, fq = lane >> 4;
;   const u16* proj = p.proj;
;   u16* Kb0 = (u16*)smem;                u16* Vb0 = (u16*)(smem + 34816);
;   u16* Kb1 = (u16*)(smem + 71680);      u16* Vb1 = (u16*)(smem + 71680 + 34816);
;   u16* Qs = Kb1;
;   float* km = (float*)(smem + 71680 + 34816);
;   float* gate = (float*)(smem + 71680 + 34816 + 8192);
;   unsigned* selm = (unsigned*)(smem + 71680 + 34816 + 8192 + 8704);
;   const int kkey = tid >> 4, kdg = tid & 15;
;   bf16x8 pk_[4], pv_[4];
;   {
;     const long tb = (long)b * S_ + qblk * 256;
; #pragma unroll
;     for (int i = 0; i < 4; ++i) {
;       pk_[i] = *(const bf16x8*)(proj + (tb + kkey + 32 * i) * NP + C_CK + h * 128 + kdg * 8);
;       pv_[i] = *(const bf16x8*)(proj + (tb + kkey + 32 * i) * NP + C_CV + h * 128 + kdg * 8);
;     }
;   }
; #pragma unroll
;   for (int i = 0; i < 4; ++i) {
;     int ch = tid + i * 512;
;     int row = ch >> 4, dg = ch & 15;
;     *(bf16x8*)(Qs + row * 136 + dg * 8) = *(const bf16x8*)(proj + (t0 + row) * NP + C_CQ + h * 128 + dg * 8);
;   }
;   for (int i = tid; i < qblk * 128; i += 512) km[i] = p.kmean[(long)(bh * 16) * 128 + i];
;   if (tid == 0) selm[128] = 0u;
.LBB0_494:
	s_ashr_i32 s2, s26, 4
	s_sub_i32 s3, 31, s2
	s_add_i32 s6, s2, -16
	s_cmp_lt_i32 s2, 16
	s_cselect_b32 s20, s3, s6
	s_lshr_b32 s28, s20, 1
	s_lshl_b32 s2, s26, 9
	s_waitcnt vmcnt(0)
	v_mov_b32_e32 v48, v234
	s_and_b32 s29, s2, 0x1000
	s_lshl_b32 s2, s28, 8
	s_add_i32 s2, s2, s29
	v_lshrrev_b32_e32 v154, 4, v48
	v_or_b32_e32 v24, s2, v154
	s_lshl_b32 s2, s26, 7
	s_and_b32 s6, s2, 0x380
	v_mov_b64_e32 v[36:37], s[92:93]
	v_and_b32_e32 v50, 15, v48
	v_mad_u64_u32 v[0:1], s[2:3], v24, s97, v[36:37]
	s_lshl_b32 s98, s6, 1
	v_lshlrev_b32_e32 v210, 4, v50
	v_lshl_add_u64 v[0:1], v[0:1], 0, s[98:99]
	v_or_b32_e32 v8, 32, v24
	v_lshl_add_u64 v[0:1], v[0:1], 0, v[210:211]
	v_mad_u64_u32 v[8:9], s[2:3], v8, s97, v[36:37]
	v_add_co_u32_e32 v4, vcc, s68, v0
	v_lshl_add_u64 v[8:9], v[8:9], 0, s[98:99]
	v_or_b32_e32 v16, 64, v24
	v_addc_co_u32_e32 v5, vcc, 0, v1, vcc
	v_lshl_add_u64 v[8:9], v[8:9], 0, v[210:211]
	v_mad_u64_u32 v[16:17], s[2:3], v16, s97, v[36:37]
	s_lshl_b32 s27, s20, 7
	v_add_co_u32_e32 v12, vcc, s68, v8
	v_lshl_add_u64 v[16:17], v[16:17], 0, s[98:99]
	v_or_b32_e32 v24, 0x60, v24
	s_add_i32 s27, s27, s29
	v_addc_co_u32_e32 v13, vcc, 0, v9, vcc
	v_lshl_add_u64 v[16:17], v[16:17], 0, v[210:211]
	v_mad_u64_u32 v[24:25], s[2:3], v24, s97, v[36:37]
	v_add_co_u32_e32 v20, vcc, s68, v16
	v_lshl_add_u64 v[24:25], v[24:25], 0, s[98:99]
	v_lshlrev_b32_e32 v32, 4, v48
	v_or_b32_e32 v38, s27, v154
	v_addc_co_u32_e32 v21, vcc, 0, v17, vcc
	v_lshl_add_u64 v[24:25], v[24:25], 0, v[210:211]
	v_and_b32_e32 v210, 0xf0, v32
	v_mad_u64_u32 v[32:33], s[2:3], v38, s97, v[36:37]
	v_add_co_u32_e32 v28, vcc, s68, v24
	v_lshl_add_u64 v[32:33], v[32:33], 0, s[98:99]
	s_nop 0
	v_addc_co_u32_e32 v29, vcc, 0, v25, vcc
	v_lshl_add_u64 v[32:33], v[32:33], 0, v[210:211]
	v_add_co_u32_e32 v32, vcc, s57, v32
	s_nop 1
	v_addc_co_u32_e32 v33, vcc, 0, v33, vcc
	v_mul_u32_u24_e32 v155, 0x110, v154
	global_load_dwordx4 v[180:183], v[32:33], off offset:2560
	v_add3_u32 v196, s70, v210, v155
	s_lshl_b32 s10, s28, 7
	v_or_b32_e32 v32, 32, v38
	v_mad_u64_u32 v[32:33], s[2:3], v32, s97, v[36:37]
	v_lshl_add_u64 v[32:33], v[32:33], 0, s[98:99]
	v_lshl_add_u64 v[32:33], v[32:33], 0, v[210:211]
	v_add_co_u32_e32 v32, vcc, s57, v32
	s_nop 1
	v_addc_co_u32_e32 v33, vcc, 0, v33, vcc
	global_load_dwordx4 v[184:187], v[32:33], off offset:2560
	v_or_b32_e32 v32, 64, v38
	v_mad_u64_u32 v[32:33], s[2:3], v32, s97, v[36:37]
	v_lshl_add_u64 v[32:33], v[32:33], 0, s[98:99]
	v_lshl_add_u64 v[32:33], v[32:33], 0, v[210:211]
	v_add_co_u32_e32 v32, vcc, s57, v32
	s_nop 1
	v_addc_co_u32_e32 v33, vcc, 0, v33, vcc
	global_load_dwordx4 v[188:191], v[32:33], off offset:2560
	v_or_b32_e32 v32, 0x60, v38
	v_mad_u64_u32 v[32:33], s[2:3], v32, s97, v[36:37]
	v_lshl_add_u64 v[32:33], v[32:33], 0, s[98:99]
	v_lshl_add_u64 v[32:33], v[32:33], 0, v[210:211]
	v_add_co_u32_e32 v32, vcc, 0x2000, v32
	s_nop 1
	v_addc_co_u32_e32 v33, vcc, 0, v33, vcc
	global_load_dwordx4 v[192:195], v[32:33], off offset:2560
	s_and_b32 s11, s26, 15
	s_lshl_b32 s21, s11, 11
	v_add_u32_e32 v210, s21, v48
	v_lshrrev_b32_e32 v44, 7, v48
	v_and_b32_e32 v45, 0x7f, v48
	v_mul_u32_u24_e32 v44, 0x210, v44
	v_lshl_add_u32 v45, v45, 2, v44
	v_add_u32_e32 v36, 0x1e800, v45
	v_lshl_add_u64 v[40:41], v[210:211], 2, s[44:45]
	v_add_u32_e32 v37, 0x200, v48
	v_add_u32_e32 v38, 0x400, v48
	v_add_co_u32_e32 v42, vcc, 0x1000, v40
	v_add_u32_e32 v39, 0x600, v48
	s_nop 1
	v_addc_co_u32_e32 v43, vcc, 0, v41, vcc
	v_cmp_gt_u32_e32 vcc, s10, v48
	s_and_saveexec_b64 s[6:7], vcc
	global_load_dword v197, v[40:41], off
	s_mov_b64 exec, s[6:7]
	v_cmp_gt_u32_e32 vcc, s10, v37
	s_and_saveexec_b64 s[6:7], vcc
	global_load_dword v198, v[40:41], off offset:2048
	s_mov_b64 exec, s[6:7]
	v_cmp_gt_u32_e32 vcc, s10, v38
	s_and_saveexec_b64 s[6:7], vcc
	global_load_dword v199, v[42:43], off
	s_mov_b64 exec, s[6:7]
	v_cmp_gt_u32_e32 vcc, s10, v39
	s_and_saveexec_b64 s[6:7], vcc
	global_load_dword v200, v[42:43], off offset:2048
	s_mov_b64 exec, s[6:7]
	global_load_dwordx4 v[0:3], v[4:5], off offset:512
	s_nop 0
	global_load_dwordx4 v[4:7], v[4:5], off offset:2560
	s_nop 0
	global_load_dwordx4 v[8:11], v[12:13], off offset:512
	s_nop 0
	global_load_dwordx4 v[12:15], v[12:13], off offset:2560
	s_nop 0
	global_load_dwordx4 v[16:19], v[20:21], off offset:512
	s_nop 0
	global_load_dwordx4 v[20:23], v[20:21], off offset:2560
	s_nop 0
	global_load_dwordx4 v[24:27], v[28:29], off offset:512
	s_nop 0
	global_load_dwordx4 v[28:31], v[28:29], off offset:2560
	s_nop 0
	s_waitcnt vmcnt(8)
	ds_write_b128 v196, v[180:183]
	ds_write_b128 v196, v[184:187] offset:8704
	ds_write_b128 v196, v[188:191] offset:17408
	ds_write_b128 v196, v[192:195] offset:26112
	v_cmp_gt_u32_e32 vcc, s10, v48
	s_and_saveexec_b64 s[6:7], vcc
	ds_write_b32 v36, v197
	s_mov_b64 exec, s[6:7]
	v_cmp_gt_u32_e32 vcc, s10, v37
	s_and_saveexec_b64 s[6:7], vcc
	ds_write_b32 v36, v198 offset:2112
	s_mov_b64 exec, s[6:7]
	v_cmp_gt_u32_e32 vcc, s10, v38
	s_and_saveexec_b64 s[6:7], vcc
	ds_write_b32 v36, v199 offset:4224
	s_mov_b64 exec, s[6:7]
	v_cmp_gt_u32_e32 vcc, s10, v39
	s_and_saveexec_b64 s[6:7], vcc
	ds_write_b32 v36, v200 offset:6336
	s_mov_b64 exec, s[6:7]
	v_cmp_eq_u32_e32 vcc, 0, v48
	s_and_saveexec_b64 s[2:3], vcc
	v_mov_b32_e32 v32, s73
	ds_write_b32 v32, v211
	s_or_b64 exec, exec, s[2:3]
	v_and_b32_e32 v40, 0x7f, v48
	v_mad_u32_u24 v32, v40, s71, 0
	v_add_u32_e32 v32, 0x11800, v32
	s_waitcnt lgkmcnt(0)
	s_barrier
; DEVI float bfs(short h) { return __uint_as_float(((unsigned)(u16)h) << 16); }
; DEVI void moba_item(const Params& p, int l, int item) {
;     ...
;   {
;     const int q = tid & 127, part = tid >> 7;
;     float dots[4] = {0.f, 0.f, 0.f, 0.f};
; #pragma unroll
;     for (int c = 0; c < 16; ++c) {
;       const bf16x8 qv = *(const bf16x8*)(Qs + q * 136 + c * 8);
;       float qf[8];
; #pragma unroll
;       for (int e = 0; e < 8; ++e) qf[e] = bfs(qv[e]);
; #pragma unroll
;       for (int k = 0; k < 4; ++k) {
;         const int blk = part + 4 * k;
;         if (blk < qblk) {
; #pragma unroll
;           for (int e = 0; e < 8; ++e) dots[k] += qf[e] * km[blk * 128 + c * 8 + e];
;         }
;       }
;     }
; #pragma unroll
;     for (int k = 0; k < 4; ++k) {
;       const int blk = part + 4 * k;
;       if (blk < qblk) gate[q * 17 + blk] = dots[k];
;     }
;   }
	s_cmp_eq_u32 s28, 0
	s_cbranch_scc1 .Lmy_gd_done
	v_and_b32_e32 v35, 63, v48
	v_lshrrev_b32_e32 v36, 6, v48
	v_and_b32_e32 v37, 15, v35
	v_lshrrev_b32_e32 v38, 4, v35
	v_lshl_add_u32 v39, v36, 4, v37
	v_mul_u32_u24_e32 v32, 0x110, v39
	v_mul_u32_u24_e32 v33, 0x210, v37
	v_mov_b32_e32 v34, s96
	v_lshl_add_u32 v32, v38, 6, v32
	v_lshl_add_u32 v33, v38, 7, v33
	v_mad_u32_u24 v34, v39, s74, v34
	v_add_u32_e32 v32, 0x11800, v32
	v_add_u32_e32 v33, 0x1e800, v33
	v_lshl_add_u32 v34, v38, 4, v34
	ds_read_b128 v[56:59], v32
	ds_read_b128 v[72:75], v33
	ds_read_b128 v[76:79], v33 offset:16
	ds_read_b128 v[60:63], v32 offset:16
	ds_read_b128 v[80:83], v33 offset:32
	ds_read_b128 v[84:87], v33 offset:48
	ds_read_b128 v[64:67], v32 offset:32
	ds_read_b128 v[88:91], v33 offset:64
	ds_read_b128 v[92:95], v33 offset:80
	ds_read_b128 v[68:71], v32 offset:48
	ds_read_b128 v[96:99], v33 offset:96
	ds_read_b128 v[100:103], v33 offset:112
	v_mov_b32_e32 v136, 0
	v_mov_b32_e32 v137, 0
	v_mov_b32_e32 v138, 0
	v_mov_b32_e32 v139, 0
	s_waitcnt lgkmcnt(9)
	v_lshlrev_b32_e32 v104, 16, v56
	v_and_b32_e32 v105, 0xffff0000, v56
	v_lshlrev_b32_e32 v106, 16, v57
	v_and_b32_e32 v107, 0xffff0000, v57
	v_lshlrev_b32_e32 v108, 16, v58
	v_and_b32_e32 v109, 0xffff0000, v58
	v_lshlrev_b32_e32 v110, 16, v59
	v_and_b32_e32 v111, 0xffff0000, v59
	v_mfma_f32_16x16x4_f32 v[136:139], v72, v104, v[136:139]
	v_mfma_f32_16x16x4_f32 v[136:139], v73, v105, v[136:139]
	v_mfma_f32_16x16x4_f32 v[136:139], v74, v106, v[136:139]
	v_mfma_f32_16x16x4_f32 v[136:139], v75, v107, v[136:139]
	v_mfma_f32_16x16x4_f32 v[136:139], v76, v108, v[136:139]
	v_mfma_f32_16x16x4_f32 v[136:139], v77, v109, v[136:139]
	v_mfma_f32_16x16x4_f32 v[136:139], v78, v110, v[136:139]
	v_mfma_f32_16x16x4_f32 v[136:139], v79, v111, v[136:139]
	s_waitcnt lgkmcnt(6)
	v_lshlrev_b32_e32 v112, 16, v60
	v_and_b32_e32 v113, 0xffff0000, v60
	v_lshlrev_b32_e32 v114, 16, v61
	v_and_b32_e32 v115, 0xffff0000, v61
	v_lshlrev_b32_e32 v116, 16, v62
	v_and_b32_e32 v117, 0xffff0000, v62
	v_lshlrev_b32_e32 v118, 16, v63
	v_and_b32_e32 v119, 0xffff0000, v63
	v_mfma_f32_16x16x4_f32 v[136:139], v80, v112, v[136:139]
	v_mfma_f32_16x16x4_f32 v[136:139], v81, v113, v[136:139]
	v_mfma_f32_16x16x4_f32 v[136:139], v82, v114, v[136:139]
	v_mfma_f32_16x16x4_f32 v[136:139], v83, v115, v[136:139]
	v_mfma_f32_16x16x4_f32 v[136:139], v84, v116, v[136:139]
	v_mfma_f32_16x16x4_f32 v[136:139], v85, v117, v[136:139]
	v_mfma_f32_16x16x4_f32 v[136:139], v86, v118, v[136:139]
	v_mfma_f32_16x16x4_f32 v[136:139], v87, v119, v[136:139]
	s_waitcnt lgkmcnt(3)
	v_lshlrev_b32_e32 v120, 16, v64
	v_and_b32_e32 v121, 0xffff0000, v64
	v_lshlrev_b32_e32 v122, 16, v65
	v_and_b32_e32 v123, 0xffff0000, v65
	v_lshlrev_b32_e32 v124, 16, v66
	v_and_b32_e32 v125, 0xffff0000, v66
	v_lshlrev_b32_e32 v126, 16, v67
	v_and_b32_e32 v127, 0xffff0000, v67
	v_mfma_f32_16x16x4_f32 v[136:139], v88, v120, v[136:139]
	v_mfma_f32_16x16x4_f32 v[136:139], v89, v121, v[136:139]
	v_mfma_f32_16x16x4_f32 v[136:139], v90, v122, v[136:139]
	v_mfma_f32_16x16x4_f32 v[136:139], v91, v123, v[136:139]
	v_mfma_f32_16x16x4_f32 v[136:139], v92, v124, v[136:139]
	v_mfma_f32_16x16x4_f32 v[136:139], v93, v125, v[136:139]
	v_mfma_f32_16x16x4_f32 v[136:139], v94, v126, v[136:139]
	v_mfma_f32_16x16x4_f32 v[136:139], v95, v127, v[136:139]
	s_waitcnt lgkmcnt(0)
	v_lshlrev_b32_e32 v128, 16, v68
	v_and_b32_e32 v129, 0xffff0000, v68
	v_lshlrev_b32_e32 v130, 16, v69
	v_and_b32_e32 v131, 0xffff0000, v69
	v_lshlrev_b32_e32 v132, 16, v70
	v_and_b32_e32 v133, 0xffff0000, v70
	v_lshlrev_b32_e32 v134, 16, v71
	v_and_b32_e32 v135, 0xffff0000, v71
	v_mfma_f32_16x16x4_f32 v[136:139], v96, v128, v[136:139]
	v_mfma_f32_16x16x4_f32 v[136:139], v97, v129, v[136:139]
	v_mfma_f32_16x16x4_f32 v[136:139], v98, v130, v[136:139]
	v_mfma_f32_16x16x4_f32 v[136:139], v99, v131, v[136:139]
	v_mfma_f32_16x16x4_f32 v[136:139], v100, v132, v[136:139]
	v_mfma_f32_16x16x4_f32 v[136:139], v101, v133, v[136:139]
	v_mfma_f32_16x16x4_f32 v[136:139], v102, v134, v[136:139]
	v_mfma_f32_16x16x4_f32 v[136:139], v103, v135, v[136:139]
	s_nop 9
	ds_write2_b32 v34, v136, v137 offset1:1
	ds_write2_b32 v34, v138, v139 offset0:2 offset1:3
